# MLA: long query block first (L2 reuse of K/V tiles across the 8 blocks of a head) + LDS fragment reads software-pipelined against MFMAs + final phase pipelined
# speedup vs baseline: 1.0024x; 1.0024x over previous
; DI void mla_block(const Params& p, LAS unsigned char* lds, int b, int hd, int qb, int tid) {
;     ...
;     const int wu = __builtin_amdgcn_readfirstlane(tid >> 6), lane = tid & 63, r = lane & 31, h = lane >> 5;
;     const int q0 = qb * 256 + wu * 32;
;     const bf16_t* QN = (const bf16_t*)(p.ws + OFF_QN); const bf16_t* QR = (const bf16_t*)(p.ws + OFF_QR);
;     const size_t tok0 = (size_t)b * S_;
;     bf16x8 qf[12];
;     {
;         const size_t qrow = tok0 + q0 + r;
; #pragma unroll
;         for (int ks = 0; ks < 8; ++ks) qf[ks] = *(const bf16x8*)(QN + qrow * 512 + hd * 128 + ks * 16 + h * 8);
; #pragma unroll
;         for (int ks = 0; ks < 4; ++ks) qf[8 + ks] = *(const bf16x8*)(QR + qrow * 256 + hd * 64 + ks * 16 + h * 8);
;     }
;     unsigned goff[6];
; #pragma unroll
;     for (int j = 0; j < 6; ++j) {
;         const int pc = wu + 8 * j; goff[j] = 0;
;         if (pc < 25) {
;             const int c = pc * 64 + lane, lr = c / 25; int cc = c - lr * 25; if (cc == 24) cc = 0;
;             const int k32 = lr & 31, key = (lr & 32) + 16 * ((k32 >> 2) & 1) + (k32 & 3) + 4 * (k32 >> 3);
;             const unsigned tok = (unsigned)(b * S_ + key);
;             goff[j] = (cc < 16) ? (unsigned)OFF_KN + (tok * 512u + hd * 128 + cc * 8) * 2u : (unsigned)OFF_PROJ + (tok * 2048u + 1920 + (cc - 16) * 8) * 2u;
;         } else if (pc < 43) {
;             const int c = (pc - 25) * 64 + lane, d = c / 9; int cc = c - d * 9; if (cc == 8) cc = 0;
;             goff[j] = (unsigned)OFF_VMT + ((unsigned)((b * 4 + hd) * 128 + d) * (unsigned)S_ + cc * 8) * 2u;
;     ...
;         const int xcd = it & 7, local = (it >> 3) & 63;
;         const int bh = xcd * 8 + (local >> 3), pr = local & 7;
;         mla_block(p, lds, bh >> 2, bh & 3, pr, tid);
;         mla_block(p, lds, bh >> 2, bh & 3, 15 - pr, tid);
.LBB0_553:
	s_lshl_b32 s0, s17, 3
	s_lshr_b32 s1, s17, 6
	s_and_b32 s0, s0, 56
	s_and_b32 s1, s1, 4
	v_mov_b32_e32 v0, v184
	s_or_b32 s4, s0, s1
	s_bfe_u32 s21, s17, 0x30003
	s_xor_b32 s21, s21, 15
	v_readfirstlane_b32 s0, v0
	s_ashr_i32 s1, s0, 6
	s_lshl_b32 s2, s21, 8
	s_lshl_b32 s6, s1, 5
	s_add_i32 s6, s6, s2
	s_bfe_u32 s5, s17, 0x20006
	s_lshl_b32 s18, s4, 10
	s_ashr_i32 s2, s6, 31
	s_add_u32 s3, s6, s18
	v_and_b32_e32 v2, 31, v0
	s_addc_u32 s2, s2, 0
	v_or_b32_e32 v160, s3, v2
	v_mov_b32_e32 v161, s2
	v_lshlrev_b64 v[4:5], 10, v[160:161]
	v_bfe_u32 v165, v0, 5, 1
	v_lshl_add_u64 v[4:5], s[58:59], 0, v[4:5]
	s_lshl_b32 s2, s5, 8
	s_mov_b32 s3, s13
	v_lshl_add_u64 v[4:5], v[4:5], 0, s[2:3]
	v_lshlrev_b32_e32 v162, 4, v165
	v_mov_b32_e32 v163, v1
	v_lshl_add_u64 v[4:5], v[4:5], 0, v[162:163]
	global_load_dwordx4 v[112:115], v[4:5], off
	global_load_dwordx4 v[116:119], v[4:5], off offset:32
	global_load_dwordx4 v[120:123], v[4:5], off offset:64
	global_load_dwordx4 v[124:127], v[4:5], off offset:96
	global_load_dwordx4 v[128:131], v[4:5], off offset:128
	global_load_dwordx4 v[132:135], v[4:5], off offset:160
	global_load_dwordx4 v[136:139], v[4:5], off offset:192
	global_load_dwordx4 v[140:143], v[4:5], off offset:224
	v_lshlrev_b64 v[4:5], 9, v[160:161]
	s_lshl_b32 s12, s5, 7
	v_lshl_add_u64 v[4:5], s[60:61], 0, v[4:5]
	v_lshl_add_u64 v[4:5], v[4:5], 0, s[12:13]
	v_lshl_add_u64 v[4:5], v[4:5], 0, v[162:163]
	global_load_dwordx4 v[144:147], v[4:5], off
	global_load_dwordx4 v[148:151], v[4:5], off offset:32
	global_load_dwordx4 v[152:155], v[4:5], off offset:64
	global_load_dwordx4 v[156:159], v[4:5], off offset:96
	s_or_b32 s3, s4, s5
	v_and_b32_e32 v163, 63, v0
	s_lshl_b32 s20, s3, 7
	v_or_b32_e32 v3, 0xfffff9c0, v163
	v_writelane_b32 v255, s5, 39
	s_cmp_gt_i32 s1, 24
	s_mov_b64 s[4:5], -1
	s_cbranch_scc0 .LBB0_577
	s_cmp_gt_u32 s1, 42
	v_mov_b32_e32 v166, 0
	s_cbranch_scc1 .LBB0_556
	s_and_b32 s3, s0, 0xffffffc0
	v_add_u32_e32 v4, s3, v3
	s_mov_b32 s3, 0x38e38e39
	v_mul_hi_u32 v5, v4, s3
	v_lshrrev_b32_e32 v6, 1, v5
	v_mad_u64_u32 v[4:5], s[4:5], v6, -9, v[4:5]
	v_lshlrev_b32_e32 v5, 4, v4
	v_cmp_ne_u32_e32 vcc, 8, v4
	s_nop 1
	v_cndmask_b32_e32 v4, 0, v5, vcc
	v_add_lshl_u32 v5, v6, s20, 13
	v_add3_u32 v166, v5, v4, s16

; DI f32x16 zero16() { f32x16 z; for (int i = 0; i < 16; ++i) z[i] = 0.f; return z; }
; DI void mla_s_softmax(const LAS unsigned char* base, int r, int h, bool is_diag, int lim, const bf16x8 (&qf)[12], f32x16 (&o)[4], float& m_run, float& l_run,
;                       bf16x8 (&pf0)[2], bf16x8 (&pf1)[2]) {
;     ...
;     if (is_diag) {
; #pragma unroll
;         for (int i = 0; i < 16; ++i) { if (16 * h + i > lim) s0[i] = -1e30f; if (32 + 16 * h + i > lim) s1[i] = -1e30f; }
; DI void mla_block(const Params& p, LAS unsigned char* lds, int b, int hd, int qb, int tid) {
;     ...
;     f32x16 o[4]; for (int dt = 0; dt < 4; ++dt) o[dt] = zero16();
;     float m_run = -1e30f, l_run = 0.f;
;     const int ntiles = 4 * qb + 4, wlast = q0 >> 6;
;     __syncthreads();
;     MLA_STAGE(0, 0);
;     const bool late = wu >= 4;
;     bf16x8 pf0[2], pf1[2];
;     int bcur = 0;
.LBB0_621:
	s_brev_b32 s9, 8
	v_cmp_gt_u32_e32 vcc, s9, v166
	s_lshr_b32 s0, s17, 3
	s_and_b32 s0, s0, 7
	s_xor_b32 s0, s0, 15
	v_cndmask_b32_e64 v32, 16, 18, vcc
	v_cmp_gt_u32_e32 vcc, s16, v166
	s_lshl_b32 s2, s21, 2
	s_lshl_b32 s0, s0, 2
	v_cndmask_b32_e32 v176, 7, v32, vcc
	v_cmp_gt_u32_e32 vcc, s9, v167
	s_add_i32 s74, s2, 4
	s_add_i32 s0, s0, 4
	v_cndmask_b32_e64 v32, 16, 18, vcc
	v_cmp_gt_u32_e32 vcc, s16, v167
	s_ashr_i32 s33, s6, 6
	v_writelane_b32 v255, s17, 46
	v_cndmask_b32_e32 v177, 7, v32, vcc
	v_cmp_gt_u32_e32 vcc, s9, v168
	s_cmp_gt_i32 s1, 3
	v_writelane_b32 v255, s21, 47
	v_cndmask_b32_e64 v32, 16, 18, vcc
	v_cmp_gt_u32_e32 vcc, s16, v168
	s_cselect_b64 s[78:79], -1, 0
	s_cmp_lt_i32 s1, 4
	v_cndmask_b32_e32 v178, 7, v32, vcc
	v_cmp_gt_u32_e32 vcc, s9, v169
	v_writelane_b32 v255, s2, 48
	s_cselect_b64 s[2:3], -1, 0
	v_cndmask_b32_e64 v32, 16, 18, vcc
	v_cmp_gt_u32_e32 vcc, s16, v169
	v_and_b32_e32 v173, 32, v0
	v_or_b32_e32 v0, s6, v2
	v_cndmask_b32_e32 v179, 7, v32, vcc
	v_cmp_gt_u32_e32 vcc, s9, v170
	s_andn2_b32 s6, s6, 63
	s_mov_b64 s[12:13], s[84:85]
	s_lshl_b32 s1, s1, 10
	v_cndmask_b32_e64 v32, 16, 18, vcc
	v_cmp_gt_u32_e32 vcc, s16, v170
	v_subrev_u32_e32 v0, s6, v0
	s_mov_b64 s[14:15], s[86:87]
	v_or_b32_e32 v14, 7, v162
	v_or_b32_e32 v15, 39, v162
	v_writelane_b32 v255, s1, 11
	s_lshl_b32 s85, s4, 10
	s_lshl_b32 s72, s5, 10
	v_cndmask_b32_e32 v180, 7, v32, vcc
	v_cmp_gt_u32_e32 vcc, s9, v171
	v_cmp_gt_i32_e64 s[4:5], v162, v0
	v_mul_u32_u24_e32 v172, 0x90, v2
	v_mul_u32_u24_e32 v174, 0x190, v2
	v_or_b32_e32 v2, 32, v162
	v_or_b32_e32 v3, 33, v162
	v_or_b32_e32 v4, 2, v162
	v_or_b32_e32 v5, 34, v162
	v_or_b32_e32 v6, 3, v162
	v_or_b32_e32 v7, 35, v162
	v_or_b32_e32 v8, 4, v162
	v_or_b32_e32 v9, 36, v162
	v_or_b32_e32 v10, 5, v162
	v_or_b32_e32 v11, 37, v162
	v_or_b32_e32 v12, 6, v162
	v_or_b32_e32 v13, 38, v162
	v_or_b32_e32 v16, 8, v162
	v_or_b32_e32 v17, 40, v162
	v_or_b32_e32 v18, 9, v162
	v_or_b32_e32 v19, 41, v162
	v_or_b32_e32 v20, 10, v162
	v_or_b32_e32 v21, 42, v162
	v_or_b32_e32 v22, 11, v162
	v_or_b32_e32 v23, 43, v162
	v_or_b32_e32 v24, 12, v162
	v_or_b32_e32 v25, 44, v162
	s_waitcnt vmcnt(0)
	v_or_b32_e32 v26, 13, v162
	v_or_b32_e32 v27, 45, v162
	v_or_b32_e32 v28, 14, v162
	v_or_b32_e32 v29, 46, v162
	v_or_b32_e32 v30, 15, v162
	v_or_b32_e32 v31, 47, v162
	v_cndmask_b32_e64 v32, 16, 18, vcc
	v_cmp_gt_u32_e32 vcc, s16, v171
	v_writelane_b32 v255, s4, 49
	v_cmp_gt_i32_e64 s[34:35], v14, v0
	v_cmp_gt_i32_e64 s[36:37], v15, v0
	v_mov_b32_e32 v14, v1
	v_mov_b32_e32 v15, v1
	s_lshl_b32 s75, s7, 10
	s_lshl_b32 s1, s8, 10
	v_cndmask_b32_e32 v181, 7, v32, vcc
	v_writelane_b32 v255, s5, 50
	v_cmp_gt_i32_e64 s[6:7], v2, v0
	v_cmp_lt_i32_e64 s[8:9], v162, v0
	v_cmp_gt_i32_e64 s[10:11], v3, v0
	v_cmp_gt_i32_e64 s[86:87], v4, v0
	v_cmp_gt_i32_e64 s[4:5], v5, v0
	v_cmp_gt_i32_e64 s[16:17], v6, v0
	v_cmp_gt_i32_e64 s[18:19], v7, v0
	v_cmp_gt_i32_e64 s[20:21], v8, v0
	v_cmp_gt_i32_e64 s[22:23], v9, v0
	v_cmp_gt_i32_e64 s[24:25], v10, v0
	v_cmp_gt_i32_e64 s[26:27], v11, v0
	v_cmp_gt_i32_e64 s[28:29], v12, v0
	v_cmp_gt_i32_e64 s[30:31], v13, v0
	v_cmp_gt_i32_e64 s[38:39], v16, v0
	v_cmp_gt_i32_e64 s[40:41], v17, v0
	v_cmp_gt_i32_e64 s[42:43], v18, v0
	v_cmp_gt_i32_e64 s[44:45], v19, v0
	v_cmp_gt_i32_e64 s[46:47], v20, v0
	v_cmp_gt_i32_e64 s[48:49], v21, v0
	v_cmp_gt_i32_e64 s[50:51], v22, v0
	v_cmp_gt_i32_e64 s[52:53], v23, v0
	v_cmp_gt_i32_e64 s[54:55], v24, v0
	v_cmp_gt_i32_e64 s[56:57], v25, v0
	v_cmp_gt_i32_e64 s[58:59], v26, v0
	v_cmp_gt_i32_e64 s[60:61], v27, v0
	v_cmp_gt_i32_e64 s[62:63], v28, v0
	v_cmp_gt_i32_e64 s[64:65], v29, v0
	v_cmp_gt_i32_e64 s[66:67], v30, v0
	v_cmp_gt_i32_e64 s[68:69], v31, v0
	v_mov_b32_e32 v0, v1
	v_mov_b32_e32 v2, v1
	v_mov_b32_e32 v3, v1
	v_mov_b32_e32 v4, v1
	v_mov_b32_e32 v5, v1
	v_mov_b32_e32 v6, v1
	v_mov_b32_e32 v7, v1
	v_mov_b32_e32 v8, v1
	v_mov_b32_e32 v9, v1
	v_mov_b32_e32 v10, v1
	v_mov_b32_e32 v11, v1
	v_mov_b32_e32 v12, v1
	v_mov_b32_e32 v13, v1
	v_mov_b64_e32 v[30:31], v[14:15]
	v_mov_b64_e32 v[46:47], v[14:15]
	v_mov_b64_e32 v[62:63], v[14:15]
	v_mov_b64_e32 v[78:79], v[14:15]
	s_add_i32 s84, s33, 1
	v_add3_u32 v182, 0, v172, v173
	s_mov_b32 s73, 0
	v_mov_b32_e32 v183, 0xf149f2ca
	v_mov_b32_e32 v175, 0
	v_mov_b64_e32 v[28:29], v[12:13]
	v_mov_b64_e32 v[26:27], v[10:11]
	v_mov_b64_e32 v[24:25], v[8:9]
	v_mov_b64_e32 v[22:23], v[6:7]
	v_mov_b64_e32 v[20:21], v[4:5]
	v_mov_b64_e32 v[18:19], v[2:3]
	v_mov_b64_e32 v[16:17], v[0:1]
	v_mov_b64_e32 v[44:45], v[12:13]
	v_mov_b64_e32 v[42:43], v[10:11]
	v_mov_b64_e32 v[40:41], v[8:9]
	v_mov_b64_e32 v[38:39], v[6:7]
	v_mov_b64_e32 v[36:37], v[4:5]
	v_mov_b64_e32 v[34:35], v[2:3]
	v_mov_b64_e32 v[32:33], v[0:1]
	v_mov_b64_e32 v[60:61], v[12:13]
	v_mov_b64_e32 v[58:59], v[10:11]
	v_mov_b64_e32 v[56:57], v[8:9]
	v_mov_b64_e32 v[54:55], v[6:7]
	v_mov_b64_e32 v[52:53], v[4:5]
	v_mov_b64_e32 v[50:51], v[2:3]
	v_mov_b64_e32 v[48:49], v[0:1]
	s_mov_b32 s77, 0
	v_mov_b64_e32 v[76:77], v[12:13]
	v_mov_b64_e32 v[74:75], v[10:11]
	v_mov_b64_e32 v[72:73], v[8:9]
	v_mov_b64_e32 v[70:71], v[6:7]
	v_mov_b64_e32 v[68:69], v[4:5]
	v_mov_b64_e32 v[66:67], v[2:3]
	v_mov_b64_e32 v[64:65], v[0:1]

; #define LAS __attribute__((address_space(3)))
; #define MFMA32(a, b, c) __builtin_amdgcn_mfma_f32_32x32x16_bf16((a), (b), (c), 0, 0, 0)
; DI void mla_pv(const LAS unsigned char* base, int r, int h, const bf16x8 (&pf0)[2], const bf16x8 (&pf1)[2], f32x16 (&o)[4]) {
;     const LAS unsigned char* vp = base + MLA_KBYTES + r * MLA_VROW + h * 32;
; #pragma unroll
;     for (int s = 0; s < 2; ++s) {
;         bf16x8 va[4], vb[4];
; #pragma unroll
;         for (int dt = 0; dt < 4; ++dt) { va[dt] = *(const LAS bf16x8*)(vp + dt * 32 * MLA_VROW + s * 16); vb[dt] = *(const LAS bf16x8*)(vp + dt * 32 * MLA_VROW + 64 + s * 16); }
;         __builtin_amdgcn_sched_barrier(0);
; #pragma unroll
;         for (int dt = 0; dt < 4; ++dt) o[dt] = MFMA32(va[dt], pf0[s], o[dt]);
; #pragma unroll
;         for (int dt = 0; dt < 4; ++dt) o[dt] = MFMA32(vb[dt], pf1[s], o[dt]);
;         __builtin_amdgcn_sched_barrier(0);
;     }
; }
; DI void mla_block(const Params& p, LAS unsigned char* lds, int b, int hd, int qb, int tid) {
;     ...
;         if (late && kt >= 1 && kt - 1 <= wlast) mla_pv(lds + bprev * MLA_BUF, r, h, pf0, pf1, o);
.LBB0_635:
	s_cmp_lg_u32 s77, 0
	s_cselect_b64 s[90:91], -1, 0
	s_and_b64 s[90:91], s[78:79], s[90:91]
	s_cmp_le_i32 s77, s84
	s_cselect_b64 vcc, -1, 0
	s_and_b64 s[90:91], s[90:91], vcc
	s_andn2_b64 vcc, exec, s[90:91]
	s_mul_i32 s89, s73, 0xac00
	s_cbranch_vccnz .LBB0_638
	s_add_i32 s90, s89, 0xffff5400
	s_cmp_lg_u32 s73, 0
	s_cselect_b32 s73, s90, 0x15800
	v_add_u32_e32 v0, s73, v182
	ds_read_b128 v[84:87], v0 offset:25600
	ds_read_b128 v[88:91], v0 offset:25664
	ds_read_b128 v[92:95], v0 offset:30208
	ds_read_b128 v[96:99], v0 offset:30272
	ds_read_b128 v[100:103], v0 offset:34816
	ds_read_b128 v[104:107], v0 offset:34880
	ds_read_b128 v[108:111], v0 offset:39424
	ds_read_b128 v[186:189], v0 offset:39488
	ds_read_b128 v[200:203], v0 offset:25616
	ds_read_b128 v[204:207], v0 offset:25680
	ds_read_b128 v[208:211], v0 offset:30224
	ds_read_b128 v[212:215], v0 offset:30288
	ds_read_b128 v[216:219], v0 offset:34832
	ds_read_b128 v[220:223], v0 offset:34896
	ds_read_b128 v[224:227], v0 offset:39440
	ds_read_b128 v[228:231], v0 offset:39504
	s_waitcnt lgkmcnt(8)
	v_mfma_f32_32x32x16_bf16 v[64:79], v[84:87], v[80:83], v[64:79]
	v_mfma_f32_32x32x16_bf16 v[48:63], v[92:95], v[80:83], v[48:63]
	v_mfma_f32_32x32x16_bf16 v[32:47], v[100:103], v[80:83], v[32:47]
	v_mfma_f32_32x32x16_bf16 v[16:31], v[108:111], v[80:83], v[16:31]
	v_mfma_f32_32x32x16_bf16 v[64:79], v[88:91], v[6:9], v[64:79]
	v_mfma_f32_32x32x16_bf16 v[48:63], v[96:99], v[6:9], v[48:63]
	v_mfma_f32_32x32x16_bf16 v[32:47], v[104:107], v[6:9], v[32:47]
	v_mfma_f32_32x32x16_bf16 v[16:31], v[186:189], v[6:9], v[16:31]
	s_waitcnt lgkmcnt(0)
	v_mfma_f32_32x32x16_bf16 v[64:79], v[200:203], v[10:13], v[64:79]
	v_mfma_f32_32x32x16_bf16 v[48:63], v[208:211], v[10:13], v[48:63]
	v_mfma_f32_32x32x16_bf16 v[32:47], v[216:219], v[10:13], v[32:47]
	v_mfma_f32_32x32x16_bf16 v[16:31], v[224:227], v[10:13], v[16:31]
	v_mfma_f32_32x32x16_bf16 v[64:79], v[204:207], v[2:5], v[64:79]
	v_mfma_f32_32x32x16_bf16 v[48:63], v[212:215], v[2:5], v[48:63]
	v_mfma_f32_32x32x16_bf16 v[32:47], v[220:223], v[2:5], v[32:47]
	v_mfma_f32_32x32x16_bf16 v[16:31], v[228:231], v[2:5], v[16:31]
	s_cmp_gt_i32 s77, s33
	s_cbranch_scc0 .LBB0_639

; #define LAS __attribute__((address_space(3)))
; DI f32x16 zero16() { f32x16 z; for (int i = 0; i < 16; ++i) z[i] = 0.f; return z; }
; #define MFMA32(a, b, c) __builtin_amdgcn_mfma_f32_32x32x16_bf16((a), (b), (c), 0, 0, 0)
; DI void mla_s_softmax(const LAS unsigned char* base, int r, int h, bool is_diag, int lim, const bf16x8 (&qf)[12], f32x16 (&o)[4], float& m_run, float& l_run,
;                       bf16x8 (&pf0)[2], bf16x8 (&pf1)[2]) {
;     f32x16 s0 = zero16(), s1 = zero16();
;     const LAS unsigned char* kp = base + r * MLA_KROW + h * 16;
; #pragma unroll
;     for (int g = 0; g < 3; ++g) {
;         bf16x8 fa[4], fb[4];
; #pragma unroll
;         for (int j = 0; j < 4; ++j) { fa[j] = *(const LAS bf16x8*)(kp + (4 * g + j) * 32); fb[j] = *(const LAS bf16x8*)(kp + 32 * MLA_KROW + (4 * g + j) * 32); }
;         __builtin_amdgcn_sched_barrier(0);
; #pragma unroll
;         for (int j = 0; j < 4; ++j) { s0 = MFMA32(fa[j], qf[4 * g + j], s0); s1 = MFMA32(fb[j], qf[4 * g + j], s1); }
;         __builtin_amdgcn_sched_barrier(0);
;     }
;     if (is_diag) {
; #pragma unroll
;         for (int i = 0; i < 16; ++i) { if (16 * h + i > lim) s0[i] = -1e30f; if (32 + 16 * h + i > lim) s1[i] = -1e30f; }
; DI void mla_block(const Params& p, LAS unsigned char* lds, int b, int hd, int qb, int tid) {
;     ...
;             if (!late) mla_pv(lds + bcur * MLA_BUF, r, h, pf0, pf1, o);
.LBB0_639:
	s_add_i32 s73, s89, 0
	v_add3_u32 v0, s73, v174, v162
	ds_read_b128 v[2:5], v0
	ds_read_b128 v[6:9], v0 offset:32
	ds_read_b128 v[10:13], v0 offset:12800
	ds_read_b128 v[186:189], v0 offset:12832
	ds_read_b128 v[190:193], v0 offset:64
	ds_read_b128 v[194:197], v0 offset:96
	ds_read_b128 v[198:201], v0 offset:12864
	ds_read_b128 v[202:205], v0 offset:12896
	ds_read_b128 v[206:209], v0 offset:128
	ds_read_b128 v[210:213], v0 offset:160
	ds_read_b128 v[214:217], v0 offset:12928
	ds_read_b128 v[218:221], v0 offset:12960
	ds_read_b128 v[222:225], v0 offset:192
	ds_read_b128 v[226:229], v0 offset:224
	ds_read_b128 v[230:233], v0 offset:12992
	ds_read_b128 v[234:237], v0 offset:13024
	s_cmp_lg_u32 s33, s77
	s_waitcnt lgkmcnt(8)
	v_mfma_f32_32x32x16_bf16 v[96:111], v[2:5], v[112:115], 0
	v_mfma_f32_32x32x16_bf16 v[80:95], v[10:13], v[112:115], 0
	v_mfma_f32_32x32x16_bf16 v[96:111], v[6:9], v[116:119], v[96:111]
	v_mfma_f32_32x32x16_bf16 v[80:95], v[186:189], v[116:119], v[80:95]
	v_mfma_f32_32x32x16_bf16 v[96:111], v[190:193], v[120:123], v[96:111]
	v_mfma_f32_32x32x16_bf16 v[80:95], v[198:201], v[120:123], v[80:95]
	v_mfma_f32_32x32x16_bf16 v[96:111], v[194:197], v[124:127], v[96:111]
	v_mfma_f32_32x32x16_bf16 v[80:95], v[202:205], v[124:127], v[80:95]
	ds_read_b128 v[2:5], v0 offset:256
	ds_read_b128 v[6:9], v0 offset:288
	ds_read_b128 v[10:13], v0 offset:13056
	ds_read_b128 v[186:189], v0 offset:13088
	ds_read_b128 v[190:193], v0 offset:320
	ds_read_b128 v[194:197], v0 offset:352
	ds_read_b128 v[198:201], v0 offset:13120
	ds_read_b128 v[202:205], v0 offset:13152
	s_waitcnt lgkmcnt(8)
	v_mfma_f32_32x32x16_bf16 v[96:111], v[206:209], v[128:131], v[96:111]
	v_mfma_f32_32x32x16_bf16 v[80:95], v[214:217], v[128:131], v[80:95]
	v_mfma_f32_32x32x16_bf16 v[96:111], v[210:213], v[132:135], v[96:111]
	v_mfma_f32_32x32x16_bf16 v[80:95], v[218:221], v[132:135], v[80:95]
	v_mfma_f32_32x32x16_bf16 v[96:111], v[222:225], v[136:139], v[96:111]
	v_mfma_f32_32x32x16_bf16 v[80:95], v[230:233], v[136:139], v[80:95]
	v_mfma_f32_32x32x16_bf16 v[96:111], v[226:229], v[140:143], v[96:111]
	v_mfma_f32_32x32x16_bf16 v[80:95], v[234:237], v[140:143], v[80:95]
	s_waitcnt lgkmcnt(0)
	v_mfma_f32_32x32x16_bf16 v[96:111], v[2:5], v[144:147], v[96:111]
	v_mfma_f32_32x32x16_bf16 v[80:95], v[10:13], v[144:147], v[80:95]
	v_mfma_f32_32x32x16_bf16 v[96:111], v[6:9], v[148:151], v[96:111]
	v_mfma_f32_32x32x16_bf16 v[80:95], v[186:189], v[148:151], v[80:95]
	v_mfma_f32_32x32x16_bf16 v[96:111], v[190:193], v[152:155], v[96:111]
	v_mfma_f32_32x32x16_bf16 v[80:95], v[198:201], v[152:155], v[80:95]
	v_mfma_f32_32x32x16_bf16 v[96:111], v[194:197], v[156:159], v[96:111]
	v_mfma_f32_32x32x16_bf16 v[80:95], v[202:205], v[156:159], v[80:95]
	s_cbranch_scc1 .LBB0_641
	v_readlane_b32 s90, v255, 49
	v_readlane_b32 s91, v255, 50
	s_nop 8
	v_cndmask_b32_e64 v80, v80, v164, s[6:7]
	v_cndmask_b32_e64 v97, v164, v97, s[8:9]
	v_cndmask_b32_e64 v0, v96, v164, s[90:91]
	v_cndmask_b32_e64 v96, v0, v96, s[8:9]
	v_cndmask_b32_e64 v81, v81, v164, s[10:11]
	v_cndmask_b32_e64 v98, v98, v164, s[86:87]
	v_cndmask_b32_e64 v82, v82, v164, s[4:5]
	v_cndmask_b32_e64 v99, v99, v164, s[16:17]
	v_cndmask_b32_e64 v83, v83, v164, s[18:19]
	v_cndmask_b32_e64 v100, v100, v164, s[20:21]
	v_cndmask_b32_e64 v84, v84, v164, s[22:23]
	v_cndmask_b32_e64 v101, v101, v164, s[24:25]
	v_cndmask_b32_e64 v85, v85, v164, s[26:27]
	v_cndmask_b32_e64 v102, v102, v164, s[28:29]
	v_cndmask_b32_e64 v86, v86, v164, s[30:31]
	v_cndmask_b32_e64 v103, v103, v164, s[34:35]
	v_cndmask_b32_e64 v87, v87, v164, s[36:37]
	v_cndmask_b32_e64 v104, v104, v164, s[38:39]
	v_cndmask_b32_e64 v88, v88, v164, s[40:41]
	v_cndmask_b32_e64 v105, v105, v164, s[42:43]
	v_cndmask_b32_e64 v89, v89, v164, s[44:45]
	v_cndmask_b32_e64 v106, v106, v164, s[46:47]
	v_cndmask_b32_e64 v90, v90, v164, s[48:49]
	v_cndmask_b32_e64 v107, v107, v164, s[50:51]
	v_cndmask_b32_e64 v91, v91, v164, s[52:53]
	v_cndmask_b32_e64 v108, v108, v164, s[54:55]
	v_cndmask_b32_e64 v92, v92, v164, s[56:57]
	v_cndmask_b32_e64 v109, v109, v164, s[58:59]
	v_cndmask_b32_e64 v93, v93, v164, s[60:61]
	v_cndmask_b32_e64 v110, v110, v164, s[62:63]
	v_cndmask_b32_e64 v94, v94, v164, s[64:65]
	v_cndmask_b32_e64 v111, v111, v164, s[66:67]
	v_cndmask_b32_e64 v95, v95, v164, s[68:69]
.LBB0_641:
	s_andn2_b64 vcc, exec, s[2:3]
	s_cbranch_vccnz .Lmla_no_vpre_0
	v_add3_u32 v252, s73, v172, v173
	ds_read_b128 v[232:235], v252 offset:25616
	ds_read_b128 v[236:239], v252 offset:30224
	ds_read_b128 v[240:243], v252 offset:34832
	ds_read_b128 v[244:247], v252 offset:39440
	ds_read_b128 v[248:251], v252 offset:25680
	ds_read_b128 v[200:203], v252 offset:25600
	ds_read_b128 v[204:207], v252 offset:25664
	ds_read_b128 v[208:211], v252 offset:30208
	ds_read_b128 v[212:215], v252 offset:30272
	ds_read_b128 v[216:219], v252 offset:34816
	ds_read_b128 v[220:223], v252 offset:34880
	ds_read_b128 v[224:227], v252 offset:39424
	ds_read_b128 v[228:231], v252 offset:39488

; #define LAS __attribute__((address_space(3)))
; DI unsigned pk2(float lo, float hi) { f32x2 v = {lo, hi}; bf2_t r = __builtin_convertvector(v, bf2_t); return __builtin_bit_cast(unsigned, r); }
; #define MFMA32(a, b, c) __builtin_amdgcn_mfma_f32_32x32x16_bf16((a), (b), (c), 0, 0, 0)
; DI void mla_s_softmax(const LAS unsigned char* base, int r, int h, bool is_diag, int lim, const bf16x8 (&qf)[12], f32x16 (&o)[4], float& m_run, float& l_run,
;                       bf16x8 (&pf0)[2], bf16x8 (&pf1)[2]) {
;     ...
;     float ls = 0.f;
; #pragma unroll
;     for (int i = 0; i < 16; ++i) { s0[i] = __builtin_amdgcn_exp2f(s0[i] - m_run); s1[i] = __builtin_amdgcn_exp2f(s1[i] - m_run); ls += s0[i] + s1[i]; }
;     l_run += ls;
; #pragma unroll
;     for (int s = 0; s < 2; ++s) {
;         u32x4 a, c;
;         a.x = pk2(s0[8 * s + 0], s0[8 * s + 1]); a.y = pk2(s0[8 * s + 2], s0[8 * s + 3]); a.z = pk2(s0[8 * s + 4], s0[8 * s + 5]); a.w = pk2(s0[8 * s + 6], s0[8 * s + 7]);
;         c.x = pk2(s1[8 * s + 0], s1[8 * s + 1]); c.y = pk2(s1[8 * s + 2], s1[8 * s + 3]); c.z = pk2(s1[8 * s + 4], s1[8 * s + 5]); c.w = pk2(s1[8 * s + 6], s1[8 * s + 7]);
;         pf0[s] = __builtin_bit_cast(bf16x8, a); pf1[s] = __builtin_bit_cast(bf16x8, c);
;     }
; }
; DI void mla_pv(const LAS unsigned char* base, int r, int h, const bf16x8 (&pf0)[2], const bf16x8 (&pf1)[2], f32x16 (&o)[4]) {
;     const LAS unsigned char* vp = base + MLA_KBYTES + r * MLA_VROW + h * 32;
; #pragma unroll
;     for (int s = 0; s < 2; ++s) {
;         bf16x8 va[4], vb[4];
; #pragma unroll
;         for (int dt = 0; dt < 4; ++dt) { va[dt] = *(const LAS bf16x8*)(vp + dt * 32 * MLA_VROW + s * 16); vb[dt] = *(const LAS bf16x8*)(vp + dt * 32 * MLA_VROW + 64 + s * 16); }
;         __builtin_amdgcn_sched_barrier(0);
; #pragma unroll
;         for (int dt = 0; dt < 4; ++dt) o[dt] = MFMA32(va[dt], pf0[s], o[dt]);
; #pragma unroll
;         for (int dt = 0; dt < 4; ++dt) o[dt] = MFMA32(vb[dt], pf1[s], o[dt]);
;         __builtin_amdgcn_sched_barrier(0);
;     }
; }
.LBB0_643:
	v_sub_f32_e32 v0, v96, v183
	v_exp_f32_e32 v15, v0
	v_sub_f32_e32 v0, v80, v183
	v_sub_f32_e32 v2, v98, v183
	v_exp_f32_e32 v185, v0
	v_sub_f32_e32 v0, v97, v183
	v_exp_f32_e32 v97, v2
	v_sub_f32_e32 v2, v82, v183
	v_exp_f32_e32 v187, v2
	v_sub_f32_e32 v2, v99, v183
	v_exp_f32_e32 v96, v2
	v_sub_f32_e32 v2, v83, v183
	v_exp_f32_e32 v98, v2
	v_sub_f32_e32 v2, v100, v183
	v_exp_f32_e32 v186, v2
	v_sub_f32_e32 v2, v84, v183
	v_exp_f32_e32 v189, v2
	v_sub_f32_e32 v2, v101, v183
	v_exp_f32_e32 v84, v2
	v_sub_f32_e32 v2, v85, v183
	v_exp_f32_e32 v100, v2
	v_sub_f32_e32 v2, v102, v183
	v_exp_f32_e32 v188, v2
	v_sub_f32_e32 v2, v86, v183
	v_exp_f32_e32 v191, v2
	v_sub_f32_e32 v2, v103, v183
	v_exp_f32_e32 v86, v2
	v_sub_f32_e32 v2, v87, v183
	v_exp_f32_e32 v102, v2
	v_sub_f32_e32 v2, v104, v183
	v_exp_f32_e32 v190, v2
	v_sub_f32_e32 v2, v88, v183
	v_exp_f32_e32 v193, v2
	v_sub_f32_e32 v2, v105, v183
	v_exp_f32_e32 v88, v2
	v_sub_f32_e32 v2, v89, v183
	v_exp_f32_e32 v104, v2
	v_sub_f32_e32 v2, v106, v183
	v_exp_f32_e32 v192, v2
	v_sub_f32_e32 v2, v90, v183
	v_exp_f32_e32 v195, v2
	v_sub_f32_e32 v2, v107, v183
	v_exp_f32_e32 v90, v2
	v_sub_f32_e32 v2, v91, v183
	v_exp_f32_e32 v106, v2
	v_sub_f32_e32 v2, v108, v183
	v_exp_f32_e32 v194, v2
	v_sub_f32_e32 v2, v92, v183
	v_exp_f32_e32 v197, v2
	v_sub_f32_e32 v2, v109, v183
	v_exp_f32_e32 v92, v2
	v_sub_f32_e32 v2, v93, v183
	v_exp_f32_e32 v108, v2
	v_sub_f32_e32 v2, v110, v183
	v_exp_f32_e32 v196, v2
	v_sub_f32_e32 v2, v94, v183
	v_exp_f32_e32 v198, v2
	v_sub_f32_e32 v2, v111, v183
	v_exp_f32_e32 v14, v0
	v_sub_f32_e32 v0, v81, v183
	v_exp_f32_e32 v94, v2
	v_sub_f32_e32 v2, v95, v183
	v_exp_f32_e32 v0, v0
	v_exp_f32_e32 v110, v2
	v_cvt_pk_bf16_f32 v80, v15, v14
	v_cvt_pk_bf16_f32 v81, v97, v96
	v_cvt_pk_bf16_f32 v82, v186, v84
	v_cvt_pk_bf16_f32 v83, v188, v86
	v_cvt_pk_bf16_f32 v6, v185, v0
	v_cvt_pk_bf16_f32 v7, v187, v98
	v_cvt_pk_bf16_f32 v8, v189, v100
	v_cvt_pk_bf16_f32 v9, v191, v102
	v_cvt_pk_bf16_f32 v10, v190, v88
	v_cvt_pk_bf16_f32 v11, v192, v90
	v_cvt_pk_bf16_f32 v12, v194, v92
	v_cvt_pk_bf16_f32 v13, v196, v94
	v_cvt_pk_bf16_f32 v2, v193, v104
	v_cvt_pk_bf16_f32 v3, v195, v106
	v_cvt_pk_bf16_f32 v4, v197, v108
	s_andn2_b64 vcc, exec, s[2:3]
	v_cvt_pk_bf16_f32 v5, v198, v110
	s_cbranch_vccnz .LBB0_645
	s_waitcnt lgkmcnt(0)
	v_mfma_f32_32x32x16_bf16 v[64:79], v[200:203], v[80:83], v[64:79]
	v_mfma_f32_32x32x16_bf16 v[48:63], v[208:211], v[80:83], v[48:63]
	v_mfma_f32_32x32x16_bf16 v[32:47], v[216:219], v[80:83], v[32:47]
	v_mfma_f32_32x32x16_bf16 v[16:31], v[224:227], v[80:83], v[16:31]
	v_mfma_f32_32x32x16_bf16 v[64:79], v[204:207], v[6:9], v[64:79]
	v_mfma_f32_32x32x16_bf16 v[48:63], v[212:215], v[6:9], v[48:63]
	v_mfma_f32_32x32x16_bf16 v[32:47], v[220:223], v[6:9], v[32:47]
	v_mfma_f32_32x32x16_bf16 v[16:31], v[228:231], v[6:9], v[16:31]
	ds_read_b128 v[200:203], v252 offset:30288
	ds_read_b128 v[204:207], v252 offset:34896
	ds_read_b128 v[208:211], v252 offset:39504
	v_mfma_f32_32x32x16_bf16 v[64:79], v[232:235], v[10:13], v[64:79]
	v_mfma_f32_32x32x16_bf16 v[48:63], v[236:239], v[10:13], v[48:63]
	v_mfma_f32_32x32x16_bf16 v[32:47], v[240:243], v[10:13], v[32:47]
	v_mfma_f32_32x32x16_bf16 v[16:31], v[244:247], v[10:13], v[16:31]
	v_mfma_f32_32x32x16_bf16 v[64:79], v[248:251], v[2:5], v[64:79]
	s_waitcnt lgkmcnt(0)
	v_mfma_f32_32x32x16_bf16 v[48:63], v[200:203], v[2:5], v[48:63]
	v_mfma_f32_32x32x16_bf16 v[32:47], v[204:207], v[2:5], v[32:47]
	v_mfma_f32_32x32x16_bf16 v[16:31], v[208:211], v[2:5], v[16:31]

; #define LAS __attribute__((address_space(3)))
; #define MFMA32(a, b, c) __builtin_amdgcn_mfma_f32_32x32x16_bf16((a), (b), (c), 0, 0, 0)
; DI void mla_pv(const LAS unsigned char* base, int r, int h, const bf16x8 (&pf0)[2], const bf16x8 (&pf1)[2], f32x16 (&o)[4]) {
;     const LAS unsigned char* vp = base + MLA_KBYTES + r * MLA_VROW + h * 32;
; #pragma unroll
;     for (int s = 0; s < 2; ++s) {
;         bf16x8 va[4], vb[4];
; #pragma unroll
;         for (int dt = 0; dt < 4; ++dt) { va[dt] = *(const LAS bf16x8*)(vp + dt * 32 * MLA_VROW + s * 16); vb[dt] = *(const LAS bf16x8*)(vp + dt * 32 * MLA_VROW + 64 + s * 16); }
;         __builtin_amdgcn_sched_barrier(0);
; #pragma unroll
;         for (int dt = 0; dt < 4; ++dt) o[dt] = MFMA32(va[dt], pf0[s], o[dt]);
; #pragma unroll
;         for (int dt = 0; dt < 4; ++dt) o[dt] = MFMA32(vb[dt], pf1[s], o[dt]);
;         __builtin_amdgcn_sched_barrier(0);
;     }
; }
; DI void mla_block(const Params& p, LAS unsigned char* lds, int b, int hd, int qb, int tid) {
;     ...
;         if (late && kt >= 1 && kt - 1 <= wlast) mla_pv(lds + bprev * MLA_BUF, r, h, pf0, pf1, o);
.LBB0_737:
	s_cmp_lg_u32 s88, 0
	s_cselect_b64 s[90:91], -1, 0
	s_and_b64 s[90:91], s[78:79], s[90:91]
	s_cmp_le_i32 s88, s74
	s_cselect_b64 vcc, -1, 0
	s_and_b64 s[90:91], s[90:91], vcc
	s_andn2_b64 vcc, exec, s[90:91]
	s_mul_i32 s89, s87, 0xac00
	s_cbranch_vccnz .LBB0_740
	s_add_i32 s90, s89, 0xffff5400
	s_cmp_lg_u32 s87, 0
	s_cselect_b32 s87, s90, 0x15800
	v_add_u32_e32 v0, s87, v182
	ds_read_b128 v[84:87], v0 offset:25600
	ds_read_b128 v[88:91], v0 offset:25664
	ds_read_b128 v[92:95], v0 offset:30208
	ds_read_b128 v[96:99], v0 offset:30272
	ds_read_b128 v[100:103], v0 offset:34816
	ds_read_b128 v[104:107], v0 offset:34880
	ds_read_b128 v[108:111], v0 offset:39424
	ds_read_b128 v[186:189], v0 offset:39488
	ds_read_b128 v[200:203], v0 offset:25616
	ds_read_b128 v[204:207], v0 offset:25680
	ds_read_b128 v[208:211], v0 offset:30224
	ds_read_b128 v[212:215], v0 offset:30288
	ds_read_b128 v[216:219], v0 offset:34832
	ds_read_b128 v[220:223], v0 offset:34896
	ds_read_b128 v[224:227], v0 offset:39440
	ds_read_b128 v[228:231], v0 offset:39504
	s_waitcnt lgkmcnt(8)
	v_mfma_f32_32x32x16_bf16 v[64:79], v[84:87], v[80:83], v[64:79]
	v_mfma_f32_32x32x16_bf16 v[48:63], v[92:95], v[80:83], v[48:63]
	v_mfma_f32_32x32x16_bf16 v[32:47], v[100:103], v[80:83], v[32:47]
	v_mfma_f32_32x32x16_bf16 v[16:31], v[108:111], v[80:83], v[16:31]
	v_mfma_f32_32x32x16_bf16 v[64:79], v[88:91], v[6:9], v[64:79]
	v_mfma_f32_32x32x16_bf16 v[48:63], v[96:99], v[6:9], v[48:63]
	v_mfma_f32_32x32x16_bf16 v[32:47], v[104:107], v[6:9], v[32:47]
	v_mfma_f32_32x32x16_bf16 v[16:31], v[186:189], v[6:9], v[16:31]
	s_waitcnt lgkmcnt(0)
	v_mfma_f32_32x32x16_bf16 v[64:79], v[200:203], v[10:13], v[64:79]
	v_mfma_f32_32x32x16_bf16 v[48:63], v[208:211], v[10:13], v[48:63]
	v_mfma_f32_32x32x16_bf16 v[32:47], v[216:219], v[10:13], v[32:47]
	v_mfma_f32_32x32x16_bf16 v[16:31], v[224:227], v[10:13], v[16:31]
	v_mfma_f32_32x32x16_bf16 v[64:79], v[204:207], v[2:5], v[64:79]
	v_mfma_f32_32x32x16_bf16 v[48:63], v[212:215], v[2:5], v[48:63]
	v_mfma_f32_32x32x16_bf16 v[32:47], v[220:223], v[2:5], v[32:47]
	v_mfma_f32_32x32x16_bf16 v[16:31], v[228:231], v[2:5], v[16:31]
	s_cmp_gt_i32 s88, s33
	s_cbranch_scc0 .LBB0_741

; #define LAS __attribute__((address_space(3)))
; DI f32x16 zero16() { f32x16 z; for (int i = 0; i < 16; ++i) z[i] = 0.f; return z; }
; #define MFMA32(a, b, c) __builtin_amdgcn_mfma_f32_32x32x16_bf16((a), (b), (c), 0, 0, 0)
; DI void mla_s_softmax(const LAS unsigned char* base, int r, int h, bool is_diag, int lim, const bf16x8 (&qf)[12], f32x16 (&o)[4], float& m_run, float& l_run,
;                       bf16x8 (&pf0)[2], bf16x8 (&pf1)[2]) {
;     f32x16 s0 = zero16(), s1 = zero16();
;     const LAS unsigned char* kp = base + r * MLA_KROW + h * 16;
; #pragma unroll
;     for (int g = 0; g < 3; ++g) {
;         bf16x8 fa[4], fb[4];
; #pragma unroll
;         for (int j = 0; j < 4; ++j) { fa[j] = *(const LAS bf16x8*)(kp + (4 * g + j) * 32); fb[j] = *(const LAS bf16x8*)(kp + 32 * MLA_KROW + (4 * g + j) * 32); }
;         __builtin_amdgcn_sched_barrier(0);
; #pragma unroll
;         for (int j = 0; j < 4; ++j) { s0 = MFMA32(fa[j], qf[4 * g + j], s0); s1 = MFMA32(fb[j], qf[4 * g + j], s1); }
;         __builtin_amdgcn_sched_barrier(0);
;     }
;     if (is_diag) {
; #pragma unroll
;         for (int i = 0; i < 16; ++i) { if (16 * h + i > lim) s0[i] = -1e30f; if (32 + 16 * h + i > lim) s1[i] = -1e30f; }
; DI void mla_block(const Params& p, LAS unsigned char* lds, int b, int hd, int qb, int tid) {
;     ...
;             if (!late) mla_pv(lds + bcur * MLA_BUF, r, h, pf0, pf1, o);
.LBB0_741:
	s_add_i32 s87, s89, 0
	v_add3_u32 v0, s87, v175, v162
	ds_read_b128 v[2:5], v0
	ds_read_b128 v[6:9], v0 offset:32
	ds_read_b128 v[10:13], v0 offset:12800
	ds_read_b128 v[186:189], v0 offset:12832
	ds_read_b128 v[190:193], v0 offset:64
	ds_read_b128 v[194:197], v0 offset:96
	ds_read_b128 v[198:201], v0 offset:12864
	ds_read_b128 v[202:205], v0 offset:12896
	ds_read_b128 v[206:209], v0 offset:128
	ds_read_b128 v[210:213], v0 offset:160
	ds_read_b128 v[214:217], v0 offset:12928
	ds_read_b128 v[218:221], v0 offset:12960
	ds_read_b128 v[222:225], v0 offset:192
	ds_read_b128 v[226:229], v0 offset:224
	ds_read_b128 v[230:233], v0 offset:12992
	ds_read_b128 v[234:237], v0 offset:13024
	s_cmp_lg_u32 s33, s88
	s_waitcnt lgkmcnt(8)
	v_mfma_f32_32x32x16_bf16 v[96:111], v[2:5], v[112:115], 0
	v_mfma_f32_32x32x16_bf16 v[80:95], v[10:13], v[112:115], 0
	v_mfma_f32_32x32x16_bf16 v[96:111], v[6:9], v[116:119], v[96:111]
	v_mfma_f32_32x32x16_bf16 v[80:95], v[186:189], v[116:119], v[80:95]
	v_mfma_f32_32x32x16_bf16 v[96:111], v[190:193], v[120:123], v[96:111]
	v_mfma_f32_32x32x16_bf16 v[80:95], v[198:201], v[120:123], v[80:95]
	v_mfma_f32_32x32x16_bf16 v[96:111], v[194:197], v[124:127], v[96:111]
	v_mfma_f32_32x32x16_bf16 v[80:95], v[202:205], v[124:127], v[80:95]
	ds_read_b128 v[2:5], v0 offset:256
	ds_read_b128 v[6:9], v0 offset:288
	ds_read_b128 v[10:13], v0 offset:13056
	ds_read_b128 v[186:189], v0 offset:13088
	ds_read_b128 v[190:193], v0 offset:320
	ds_read_b128 v[194:197], v0 offset:352
	ds_read_b128 v[198:201], v0 offset:13120
	ds_read_b128 v[202:205], v0 offset:13152
	s_waitcnt lgkmcnt(8)
	v_mfma_f32_32x32x16_bf16 v[96:111], v[206:209], v[128:131], v[96:111]
	v_mfma_f32_32x32x16_bf16 v[80:95], v[214:217], v[128:131], v[80:95]
	v_mfma_f32_32x32x16_bf16 v[96:111], v[210:213], v[132:135], v[96:111]
	v_mfma_f32_32x32x16_bf16 v[80:95], v[218:221], v[132:135], v[80:95]
	v_mfma_f32_32x32x16_bf16 v[96:111], v[222:225], v[136:139], v[96:111]
	v_mfma_f32_32x32x16_bf16 v[80:95], v[230:233], v[136:139], v[80:95]
	v_mfma_f32_32x32x16_bf16 v[96:111], v[226:229], v[140:143], v[96:111]
	v_mfma_f32_32x32x16_bf16 v[80:95], v[234:237], v[140:143], v[80:95]
	s_waitcnt lgkmcnt(0)
	v_mfma_f32_32x32x16_bf16 v[96:111], v[2:5], v[144:147], v[96:111]
	v_mfma_f32_32x32x16_bf16 v[80:95], v[10:13], v[144:147], v[80:95]
	v_mfma_f32_32x32x16_bf16 v[96:111], v[6:9], v[148:151], v[96:111]
	v_mfma_f32_32x32x16_bf16 v[80:95], v[186:189], v[148:151], v[80:95]
	v_mfma_f32_32x32x16_bf16 v[96:111], v[190:193], v[152:155], v[96:111]
	v_mfma_f32_32x32x16_bf16 v[80:95], v[198:201], v[152:155], v[80:95]
	v_mfma_f32_32x32x16_bf16 v[96:111], v[194:197], v[156:159], v[96:111]
	v_mfma_f32_32x32x16_bf16 v[80:95], v[202:205], v[156:159], v[80:95]
	s_cbranch_scc1 .LBB0_743
	s_nop 9
	v_cndmask_b32_e64 v0, v96, v164, s[4:5]
	v_cndmask_b32_e64 v80, v80, v164, s[6:7]
	v_cndmask_b32_e64 v97, v164, v97, s[8:9]
	v_cndmask_b32_e64 v96, v0, v96, s[8:9]
	v_cndmask_b32_e64 v81, v81, v164, s[10:11]
	v_cndmask_b32_e64 v98, v98, v164, s[84:85]
	v_cndmask_b32_e64 v82, v82, v164, s[0:1]
	v_cndmask_b32_e64 v99, v99, v164, s[16:17]
	v_cndmask_b32_e64 v83, v83, v164, s[18:19]
	v_cndmask_b32_e64 v100, v100, v164, s[20:21]
	v_cndmask_b32_e64 v84, v84, v164, s[22:23]
	v_cndmask_b32_e64 v101, v101, v164, s[24:25]
	v_cndmask_b32_e64 v85, v85, v164, s[26:27]
	v_cndmask_b32_e64 v102, v102, v164, s[28:29]
	v_cndmask_b32_e64 v86, v86, v164, s[30:31]
	v_cndmask_b32_e64 v103, v103, v164, s[34:35]
	v_cndmask_b32_e64 v87, v87, v164, s[36:37]
	v_cndmask_b32_e64 v104, v104, v164, s[38:39]
	v_cndmask_b32_e64 v88, v88, v164, s[40:41]
	v_cndmask_b32_e64 v105, v105, v164, s[42:43]
	v_cndmask_b32_e64 v89, v89, v164, s[44:45]
	v_cndmask_b32_e64 v106, v106, v164, s[46:47]
	v_cndmask_b32_e64 v90, v90, v164, s[48:49]
	v_cndmask_b32_e64 v107, v107, v164, s[50:51]
	v_cndmask_b32_e64 v91, v91, v164, s[52:53]
	v_cndmask_b32_e64 v108, v108, v164, s[54:55]
	v_cndmask_b32_e64 v92, v92, v164, s[56:57]
	v_cndmask_b32_e64 v109, v109, v164, s[58:59]
	v_cndmask_b32_e64 v93, v93, v164, s[60:61]
	v_cndmask_b32_e64 v110, v110, v164, s[62:63]
	v_cndmask_b32_e64 v94, v94, v164, s[64:65]
	v_cndmask_b32_e64 v111, v111, v164, s[66:67]
	v_cndmask_b32_e64 v95, v95, v164, s[68:69]
.LBB0_743:
	s_andn2_b64 vcc, exec, s[2:3]
	s_cbranch_vccnz .Lmla_no_vpre_1
	v_add3_u32 v252, s87, v173, v174
	ds_read_b128 v[232:235], v252 offset:25616
	ds_read_b128 v[236:239], v252 offset:30224
	ds_read_b128 v[240:243], v252 offset:34832
	ds_read_b128 v[244:247], v252 offset:39440
	ds_read_b128 v[248:251], v252 offset:25680
	ds_read_b128 v[200:203], v252 offset:25600
	ds_read_b128 v[204:207], v252 offset:25664
	ds_read_b128 v[208:211], v252 offset:30208
	ds_read_b128 v[212:215], v252 offset:30272
	ds_read_b128 v[216:219], v252 offset:34816
	ds_read_b128 v[220:223], v252 offset:34880
	ds_read_b128 v[224:227], v252 offset:39424
	ds_read_b128 v[228:231], v252 offset:39488
